# v040 with the P5 merge-epilogue group wait split so the first half-group math starts after two of the four gate loads
# speedup vs baseline: 1.0117x; 1.0006x over previous
.LBB0_368:
	v_add_u32_e32 v253, 0x10000, v201
	ds_read_b128 v[130:133], v253
	ds_read_b128 v[134:137], v253 offset:1024
	ds_read_b128 v[138:141], v253 offset:2048
	ds_read_b128 v[142:145], v253 offset:3072
	s_add_u32 s10, s8, 0xfffc0080
	s_addc_u32 s11, s9, -1
	s_cmp_eq_u32 s29, 12
	s_cselect_b32 s11, s81, s11
	s_cselect_b32 s10, s80, s10
	s_cselect_b32 s53, s83, s28
	s_cselect_b32 s52, s82, s7
	s_add_i32 m0, s34, 0xc000
	ds_read_b128 v[146:149], v199
	ds_read_b128 v[150:153], v199 offset:1024
	ds_read_b128 v[154:157], v199 offset:2048
	ds_read_b128 v[158:161], v199 offset:3072
	ds_read_b128 v[162:165], v199 offset:4096
	ds_read_b128 v[166:169], v199 offset:5120
	ds_read_b128 v[170:173], v199 offset:6144
	ds_read_b128 v[174:177], v199 offset:7168
	global_load_lds_dwordx4 v212, s[8:9]
	s_add_i32 m0, s34, 0xe000
	s_nop 0
	global_load_lds_dwordx4 v214, s[8:9]
	s_waitcnt lgkmcnt(8)
	s_setprio 1
	s_barrier
	s_waitcnt lgkmcnt(0)
	v_mfma_f32_16x16x32_bf16 v[126:129], v[130:133], v[146:149], v[126:129]
	v_mfma_f32_16x16x32_bf16 v[122:125], v[138:141], v[146:149], v[122:125]
	v_mfma_f32_16x16x32_bf16 v[118:121], v[130:133], v[154:157], v[118:121]
	v_mfma_f32_16x16x32_bf16 v[114:117], v[138:141], v[154:157], v[114:117]
	v_mfma_f32_16x16x32_bf16 v[110:113], v[130:133], v[162:165], v[110:113]
	v_mfma_f32_16x16x32_bf16 v[106:109], v[138:141], v[162:165], v[106:109]
	v_mfma_f32_16x16x32_bf16 v[102:105], v[130:133], v[170:173], v[102:105]
	v_mfma_f32_16x16x32_bf16 v[98:101], v[138:141], v[170:173], v[98:101]
	v_mfma_f32_16x16x32_bf16 v[126:129], v[134:137], v[150:153], v[126:129]
	v_mfma_f32_16x16x32_bf16 v[122:125], v[142:145], v[150:153], v[122:125]
	v_mfma_f32_16x16x32_bf16 v[118:121], v[134:137], v[158:161], v[118:121]
	v_mfma_f32_16x16x32_bf16 v[114:117], v[142:145], v[158:161], v[114:117]
	v_mfma_f32_16x16x32_bf16 v[110:113], v[134:137], v[166:169], v[110:113]
	v_mfma_f32_16x16x32_bf16 v[106:109], v[142:145], v[166:169], v[106:109]
	v_mfma_f32_16x16x32_bf16 v[102:105], v[134:137], v[174:177], v[102:105]
	v_mfma_f32_16x16x32_bf16 v[98:101], v[142:145], v[174:177], v[98:101]
	s_barrier
	s_setprio 0
	s_mov_b32 m0, s35
	ds_read_b128 v[178:181], v253 offset:16384
	ds_read_b128 v[182:185], v253 offset:17408
	ds_read_b128 v[186:189], v253 offset:18432
	ds_read_b128 v[190:193], v253 offset:19456
	global_load_lds_dwordx4 v194, s[52:53]
	s_mov_b32 m0, s42
	s_nop 0
	global_load_lds_dwordx4 v210, s[52:53]
	s_setprio 1
	s_barrier
	s_waitcnt lgkmcnt(0)
	v_mfma_f32_16x16x32_bf16 v[94:97], v[178:181], v[146:149], v[94:97]
	v_mfma_f32_16x16x32_bf16 v[90:93], v[186:189], v[146:149], v[90:93]
	v_mfma_f32_16x16x32_bf16 v[86:89], v[178:181], v[154:157], v[86:89]
	v_mfma_f32_16x16x32_bf16 v[82:85], v[186:189], v[154:157], v[82:85]
	v_mfma_f32_16x16x32_bf16 v[78:81], v[178:181], v[162:165], v[78:81]
	v_mfma_f32_16x16x32_bf16 v[74:77], v[186:189], v[162:165], v[74:77]
	v_mfma_f32_16x16x32_bf16 v[70:73], v[178:181], v[170:173], v[70:73]
	v_mfma_f32_16x16x32_bf16 v[66:69], v[186:189], v[170:173], v[66:69]
	v_mfma_f32_16x16x32_bf16 v[94:97], v[182:185], v[150:153], v[94:97]
	v_mfma_f32_16x16x32_bf16 v[90:93], v[190:193], v[150:153], v[90:93]
	v_mfma_f32_16x16x32_bf16 v[86:89], v[182:185], v[158:161], v[86:89]
	v_mfma_f32_16x16x32_bf16 v[82:85], v[190:193], v[158:161], v[82:85]
	v_mfma_f32_16x16x32_bf16 v[78:81], v[182:185], v[166:169], v[78:81]
	v_mfma_f32_16x16x32_bf16 v[74:77], v[190:193], v[166:169], v[74:77]
	v_mfma_f32_16x16x32_bf16 v[70:73], v[182:185], v[174:177], v[70:73]
	s_mov_b32 m0, s34
	v_mfma_f32_16x16x32_bf16 v[66:69], v[190:193], v[174:177], v[66:69]
	s_barrier
	s_setprio 0
	ds_read_b128 v[146:149], v199 offset:16384
	ds_read_b128 v[150:153], v199 offset:17408
	ds_read_b128 v[154:157], v199 offset:18432
	ds_read_b128 v[158:161], v199 offset:19456
	ds_read_b128 v[162:165], v199 offset:20480
	ds_read_b128 v[166:169], v199 offset:21504
	ds_read_b128 v[170:173], v199 offset:22528
	ds_read_b128 v[174:177], v199 offset:23552
	global_load_lds_dwordx4 v206, s[10:11]
	s_mov_b32 m0, s56
	s_nop 0
	global_load_lds_dwordx4 v208, s[10:11]
	s_setprio 1
	s_barrier
	s_waitcnt lgkmcnt(0)
	v_mfma_f32_16x16x32_bf16 v[62:65], v[130:133], v[146:149], v[62:65]
	v_mfma_f32_16x16x32_bf16 v[58:61], v[138:141], v[146:149], v[58:61]
	v_mfma_f32_16x16x32_bf16 v[54:57], v[130:133], v[154:157], v[54:57]
	v_mfma_f32_16x16x32_bf16 v[50:53], v[138:141], v[154:157], v[50:53]
	v_mfma_f32_16x16x32_bf16 v[46:49], v[130:133], v[162:165], v[46:49]
	v_mfma_f32_16x16x32_bf16 v[42:45], v[138:141], v[162:165], v[42:45]
	v_mfma_f32_16x16x32_bf16 v[38:41], v[130:133], v[170:173], v[38:41]
	v_mfma_f32_16x16x32_bf16 v[34:37], v[138:141], v[170:173], v[34:37]
	v_mfma_f32_16x16x32_bf16 v[62:65], v[134:137], v[150:153], v[62:65]
	v_mfma_f32_16x16x32_bf16 v[58:61], v[142:145], v[150:153], v[58:61]
	v_mfma_f32_16x16x32_bf16 v[54:57], v[134:137], v[158:161], v[54:57]
	v_mfma_f32_16x16x32_bf16 v[50:53], v[142:145], v[158:161], v[50:53]
	v_mfma_f32_16x16x32_bf16 v[46:49], v[134:137], v[166:169], v[46:49]
	v_mfma_f32_16x16x32_bf16 v[42:45], v[142:145], v[166:169], v[42:45]
	v_mfma_f32_16x16x32_bf16 v[38:41], v[134:137], v[174:177], v[38:41]
	v_mfma_f32_16x16x32_bf16 v[34:37], v[142:145], v[174:177], v[34:37]
	s_barrier
	s_setprio 0
	s_add_u32 s86, s52, 0x40000
	s_addc_u32 s87, s53, 0
	s_mov_b32 m0, s57
	s_nop 0
	global_load_lds_dwordx4 v194, s[86:87]
	s_mov_b32 m0, s67
	s_nop 0
	global_load_lds_dwordx4 v210, s[86:87]
	s_waitcnt vmcnt(6)
	s_setprio 1
	s_barrier
	v_mfma_f32_16x16x32_bf16 v[30:33], v[178:181], v[146:149], v[30:33]
	v_mfma_f32_16x16x32_bf16 v[26:29], v[186:189], v[146:149], v[26:29]
	v_mfma_f32_16x16x32_bf16 v[22:25], v[178:181], v[154:157], v[22:25]
	v_mfma_f32_16x16x32_bf16 v[18:21], v[186:189], v[154:157], v[18:21]
	v_mfma_f32_16x16x32_bf16 v[14:17], v[178:181], v[162:165], v[14:17]
	v_mfma_f32_16x16x32_bf16 v[10:13], v[186:189], v[162:165], v[10:13]
	v_mfma_f32_16x16x32_bf16 v[6:9], v[178:181], v[170:173], v[6:9]
	v_mfma_f32_16x16x32_bf16 v[2:5], v[186:189], v[170:173], v[2:5]
	v_mfma_f32_16x16x32_bf16 v[30:33], v[182:185], v[150:153], v[30:33]
	v_mfma_f32_16x16x32_bf16 v[26:29], v[190:193], v[150:153], v[26:29]
	v_mfma_f32_16x16x32_bf16 v[22:25], v[182:185], v[158:161], v[22:25]
	v_mfma_f32_16x16x32_bf16 v[18:21], v[190:193], v[158:161], v[18:21]
	v_mfma_f32_16x16x32_bf16 v[14:17], v[182:185], v[166:169], v[14:17]
	v_mfma_f32_16x16x32_bf16 v[10:13], v[190:193], v[166:169], v[10:13]
	v_mfma_f32_16x16x32_bf16 v[6:9], v[182:185], v[174:177], v[6:9]
	v_mfma_f32_16x16x32_bf16 v[2:5], v[190:193], v[174:177], v[2:5]
	s_barrier
	s_setprio 0
	ds_read_b128 v[130:133], v253 offset:32768
	ds_read_b128 v[134:137], v253 offset:33792
	ds_read_b128 v[138:141], v253 offset:34816
	ds_read_b128 v[142:145], v253 offset:35840
	s_add_u32 s10, s10, 0x40000
	s_addc_u32 s11, s11, 0
	s_mov_b32 m0, s70
	ds_read_b128 v[146:149], v199 offset:32768
	ds_read_b128 v[150:153], v199 offset:33792
	ds_read_b128 v[154:157], v199 offset:34816
	ds_read_b128 v[158:161], v199 offset:35840
	ds_read_b128 v[162:165], v199 offset:36864
	ds_read_b128 v[166:169], v199 offset:37888
	ds_read_b128 v[170:173], v199 offset:38912
	ds_read_b128 v[174:177], v199 offset:39936
	global_load_lds_dwordx4 v206, s[10:11]
	s_mov_b32 m0, s71
	s_nop 0
	global_load_lds_dwordx4 v208, s[10:11]
	s_waitcnt lgkmcnt(8)
	s_setprio 1
	s_barrier
	s_waitcnt lgkmcnt(0)
	v_mfma_f32_16x16x32_bf16 v[126:129], v[130:133], v[146:149], v[126:129]
	v_mfma_f32_16x16x32_bf16 v[122:125], v[138:141], v[146:149], v[122:125]
	v_mfma_f32_16x16x32_bf16 v[118:121], v[130:133], v[154:157], v[118:121]
	v_mfma_f32_16x16x32_bf16 v[114:117], v[138:141], v[154:157], v[114:117]
	v_mfma_f32_16x16x32_bf16 v[110:113], v[130:133], v[162:165], v[110:113]
	v_mfma_f32_16x16x32_bf16 v[106:109], v[138:141], v[162:165], v[106:109]
	v_mfma_f32_16x16x32_bf16 v[102:105], v[130:133], v[170:173], v[102:105]
	v_mfma_f32_16x16x32_bf16 v[98:101], v[138:141], v[170:173], v[98:101]
	v_mfma_f32_16x16x32_bf16 v[126:129], v[134:137], v[150:153], v[126:129]
	v_mfma_f32_16x16x32_bf16 v[122:125], v[142:145], v[150:153], v[122:125]
	v_mfma_f32_16x16x32_bf16 v[118:121], v[134:137], v[158:161], v[118:121]
	v_mfma_f32_16x16x32_bf16 v[114:117], v[142:145], v[158:161], v[114:117]
	v_mfma_f32_16x16x32_bf16 v[110:113], v[134:137], v[166:169], v[110:113]
	v_mfma_f32_16x16x32_bf16 v[106:109], v[142:145], v[166:169], v[106:109]
	v_mfma_f32_16x16x32_bf16 v[102:105], v[134:137], v[174:177], v[102:105]
	v_mfma_f32_16x16x32_bf16 v[98:101], v[142:145], v[174:177], v[98:101]
	s_barrier
	s_setprio 0
	s_mov_b32 m0, s78
	ds_read_b128 v[178:181], v253 offset:49152
	ds_read_b128 v[182:185], v253 offset:50176
	ds_read_b128 v[186:189], v253 offset:51200
	ds_read_b128 v[190:193], v253 offset:52224
	s_add_u32 s98, s52, 0x80
	s_addc_u32 s99, s53, 0
	global_load_lds_dwordx4 v194, s[98:99]
	s_mov_b32 m0, s79
	s_nop 0
	global_load_lds_dwordx4 v210, s[98:99]
	s_setprio 1
	s_barrier
	s_waitcnt lgkmcnt(0)
	v_mfma_f32_16x16x32_bf16 v[94:97], v[178:181], v[146:149], v[94:97]
	v_mfma_f32_16x16x32_bf16 v[90:93], v[186:189], v[146:149], v[90:93]
	v_mfma_f32_16x16x32_bf16 v[86:89], v[178:181], v[154:157], v[86:89]
	v_mfma_f32_16x16x32_bf16 v[82:85], v[186:189], v[154:157], v[82:85]
	v_mfma_f32_16x16x32_bf16 v[78:81], v[178:181], v[162:165], v[78:81]
	v_mfma_f32_16x16x32_bf16 v[74:77], v[186:189], v[162:165], v[74:77]
	v_mfma_f32_16x16x32_bf16 v[70:73], v[178:181], v[170:173], v[70:73]
	v_mfma_f32_16x16x32_bf16 v[66:69], v[186:189], v[170:173], v[66:69]
	v_mfma_f32_16x16x32_bf16 v[94:97], v[182:185], v[150:153], v[94:97]
	v_mfma_f32_16x16x32_bf16 v[90:93], v[190:193], v[150:153], v[90:93]
	v_mfma_f32_16x16x32_bf16 v[86:89], v[182:185], v[158:161], v[86:89]
	v_mfma_f32_16x16x32_bf16 v[82:85], v[190:193], v[158:161], v[82:85]
	v_mfma_f32_16x16x32_bf16 v[78:81], v[182:185], v[166:169], v[78:81]
	v_mfma_f32_16x16x32_bf16 v[74:77], v[190:193], v[166:169], v[74:77]
	v_mfma_f32_16x16x32_bf16 v[70:73], v[182:185], v[174:177], v[70:73]
	s_mov_b32 m0, s26
	v_mfma_f32_16x16x32_bf16 v[66:69], v[190:193], v[174:177], v[66:69]
	s_barrier
	s_setprio 0
	ds_read_b128 v[146:149], v199 offset:49152
	ds_read_b128 v[150:153], v199 offset:50176
	ds_read_b128 v[154:157], v199 offset:51200
	ds_read_b128 v[158:161], v199 offset:52224
	ds_read_b128 v[162:165], v199 offset:53248
	ds_read_b128 v[166:169], v199 offset:54272
	ds_read_b128 v[170:173], v199 offset:55296
	ds_read_b128 v[174:177], v199 offset:56320
	s_add_u32 s100, s10, 0xfffc0080
	s_addc_u32 s101, s11, -1
	global_load_lds_dwordx4 v206, s[100:101]
	s_mov_b32 m0, s4
	s_nop 0
	global_load_lds_dwordx4 v208, s[100:101]
	s_setprio 1
	s_barrier
	s_waitcnt lgkmcnt(0)
	v_mfma_f32_16x16x32_bf16 v[62:65], v[130:133], v[146:149], v[62:65]
	v_mfma_f32_16x16x32_bf16 v[58:61], v[138:141], v[146:149], v[58:61]
	v_mfma_f32_16x16x32_bf16 v[54:57], v[130:133], v[154:157], v[54:57]
	v_mfma_f32_16x16x32_bf16 v[50:53], v[138:141], v[154:157], v[50:53]
	v_mfma_f32_16x16x32_bf16 v[46:49], v[130:133], v[162:165], v[46:49]
	v_mfma_f32_16x16x32_bf16 v[42:45], v[138:141], v[162:165], v[42:45]
	v_mfma_f32_16x16x32_bf16 v[38:41], v[130:133], v[170:173], v[38:41]
	v_mfma_f32_16x16x32_bf16 v[34:37], v[138:141], v[170:173], v[34:37]
	v_mfma_f32_16x16x32_bf16 v[62:65], v[134:137], v[150:153], v[62:65]
	v_mfma_f32_16x16x32_bf16 v[58:61], v[142:145], v[150:153], v[58:61]
	v_mfma_f32_16x16x32_bf16 v[54:57], v[134:137], v[158:161], v[54:57]
	v_mfma_f32_16x16x32_bf16 v[50:53], v[142:145], v[158:161], v[50:53]
	v_mfma_f32_16x16x32_bf16 v[46:49], v[134:137], v[166:169], v[46:49]
	v_mfma_f32_16x16x32_bf16 v[42:45], v[142:145], v[166:169], v[42:45]
	v_mfma_f32_16x16x32_bf16 v[38:41], v[134:137], v[174:177], v[38:41]
	v_mfma_f32_16x16x32_bf16 v[34:37], v[142:145], v[174:177], v[34:37]
	s_barrier
	s_setprio 0
	s_add_u32 s10, s52, 0x40080
	s_addc_u32 s11, s53, 0
	s_mov_b32 m0, s5
	s_nop 0
	global_load_lds_dwordx4 v194, s[10:11]
	s_mov_b32 m0, s58
	s_nop 0
	global_load_lds_dwordx4 v210, s[10:11]
	s_waitcnt vmcnt(6)
	s_setprio 1
	s_barrier
	v_mfma_f32_16x16x32_bf16 v[30:33], v[178:181], v[146:149], v[30:33]
	v_mfma_f32_16x16x32_bf16 v[26:29], v[186:189], v[146:149], v[26:29]
	v_mfma_f32_16x16x32_bf16 v[22:25], v[178:181], v[154:157], v[22:25]
	v_mfma_f32_16x16x32_bf16 v[18:21], v[186:189], v[154:157], v[18:21]
	v_mfma_f32_16x16x32_bf16 v[14:17], v[178:181], v[162:165], v[14:17]
	v_mfma_f32_16x16x32_bf16 v[10:13], v[186:189], v[162:165], v[10:13]
	v_mfma_f32_16x16x32_bf16 v[6:9], v[178:181], v[170:173], v[6:9]
	v_mfma_f32_16x16x32_bf16 v[2:5], v[186:189], v[170:173], v[2:5]
	v_mfma_f32_16x16x32_bf16 v[30:33], v[182:185], v[150:153], v[30:33]
	v_mfma_f32_16x16x32_bf16 v[26:29], v[190:193], v[150:153], v[26:29]
	v_mfma_f32_16x16x32_bf16 v[22:25], v[182:185], v[158:161], v[22:25]
	v_mfma_f32_16x16x32_bf16 v[18:21], v[190:193], v[158:161], v[18:21]
	v_mfma_f32_16x16x32_bf16 v[14:17], v[182:185], v[166:169], v[14:17]
	v_mfma_f32_16x16x32_bf16 v[10:13], v[190:193], v[166:169], v[10:13]
	v_mfma_f32_16x16x32_bf16 v[6:9], v[182:185], v[174:177], v[6:9]
	v_mfma_f32_16x16x32_bf16 v[2:5], v[190:193], v[174:177], v[2:5]
	s_setprio 0
	s_add_i32 s29, s29, 2
	s_add_u32 s8, s8, 0x100
	s_addc_u32 s9, s9, 0
	s_add_u32 s7, s7, 0x100
	s_addc_u32 s28, s28, 0
	s_cmp_gt_u32 s29, 13
	s_barrier
	s_cbranch_scc0 .LBB0_368
	s_cmp_gt_i32 s95, 1
	s_cselect_b64 s[52:53], -1, 0
	s_mul_i32 s7, s6, 0x680000
	s_lshl_b32 s8, s95, 12
	s_lshl_b32 s9, s54, 9
	s_add_i32 s7, s7, s8
	s_add_i32 s7, s7, s9
	s_add_i32 s7, s7, 0x3800
	s_add_u32 s20, s50, s7
	s_addc_u32 s21, s51, 0
	s_lshl_b32 s7, s6, 20
	s_add_i32 s7, s7, s9
	s_add_u32 s10, s96, s7
	s_addc_u32 s11, s97, 0
	s_mov_b32 s86, 0xbfb8aa3b
	s_mov_b32 s87, 0xbfb8aa3b
	v_mul_u32_u24_e32 v253, 0x6800, v197
	v_lshlrev_b32_e32 v255, 12, v197
	v_lshl_add_u32 v253, v203, 1, v253
	v_lshl_add_u32 v255, v203, 1, v255
	v_add_u32_e32 v254, 0x1000, v253
	s_cmp_eq_u32 s95, 2
	s_cbranch_scc1 .Lem_br2
	global_load_dwordx4 v[130:133], v253, s[20:21]
	global_load_dwordx4 v[134:137], v254, s[20:21]
	global_load_dwordx4 v[138:141], v253, s[20:21] offset:256
	global_load_dwordx4 v[142:145], v254, s[20:21] offset:256
	s_add_u32 s28, s20, 0x68000
	s_addc_u32 s29, s21, 0
	global_load_dwordx4 v[146:149], v253, s[28:29]
	global_load_dwordx4 v[150:153], v254, s[28:29]
	global_load_dwordx4 v[154:157], v253, s[28:29] offset:256
	global_load_dwordx4 v[158:161], v254, s[28:29] offset:256
	s_add_u32 s28, s20, 0xd0000
	s_addc_u32 s29, s21, 0
	global_load_dwordx4 v[162:165], v253, s[28:29]
	global_load_dwordx4 v[166:169], v254, s[28:29]
	global_load_dwordx4 v[170:173], v253, s[28:29] offset:256
	global_load_dwordx4 v[174:177], v254, s[28:29] offset:256
	s_add_u32 s28, s20, 0x138000
	s_addc_u32 s29, s21, 0
	global_load_dwordx4 v[178:181], v253, s[28:29]
	global_load_dwordx4 v[182:185], v254, s[28:29]
	global_load_dwordx4 v[186:189], v253, s[28:29] offset:256
	global_load_dwordx4 v[190:193], v254, s[28:29] offset:256
	s_waitcnt vmcnt(14)
	v_lshlrev_b32_e32 v216, 16, v130
	v_and_b32_e32 v217, 0xffff0000, v130
	v_lshlrev_b32_e32 v218, 16, v131
	v_and_b32_e32 v219, 0xffff0000, v131
	v_lshlrev_b32_e32 v220, 16, v132
	v_and_b32_e32 v221, 0xffff0000, v132
	v_lshlrev_b32_e32 v222, 16, v133
	v_and_b32_e32 v223, 0xffff0000, v133
	v_pk_mul_f32 v[216:217], v[216:217], s[86:87] op_sel_hi:[1,0]
	v_pk_mul_f32 v[218:219], v[218:219], s[86:87] op_sel_hi:[1,0]
	v_pk_mul_f32 v[220:221], v[220:221], s[86:87] op_sel_hi:[1,0]
	v_pk_mul_f32 v[222:223], v[222:223], s[86:87] op_sel_hi:[1,0]
	v_exp_f32_e32 v216, v216
	v_exp_f32_e32 v217, v217
	v_exp_f32_e32 v218, v218
	v_exp_f32_e32 v219, v219
	v_exp_f32_e32 v220, v220
	v_exp_f32_e32 v221, v221
	v_exp_f32_e32 v222, v222
	v_exp_f32_e32 v223, v223
	v_pk_add_f32 v[216:217], v[216:217], 1.0 op_sel_hi:[1,0]
	v_pk_add_f32 v[218:219], v[218:219], 1.0 op_sel_hi:[1,0]
	v_pk_add_f32 v[220:221], v[220:221], 1.0 op_sel_hi:[1,0]
	v_pk_add_f32 v[222:223], v[222:223], 1.0 op_sel_hi:[1,0]
	v_rcp_f32_e32 v216, v216
	v_rcp_f32_e32 v217, v217
	v_rcp_f32_e32 v218, v218
	v_rcp_f32_e32 v219, v219
	v_rcp_f32_e32 v220, v220
	v_rcp_f32_e32 v221, v221
	v_rcp_f32_e32 v222, v222
	v_rcp_f32_e32 v223, v223
	v_lshlrev_b32_e32 v242, 16, v134
	v_and_b32_e32 v243, 0xffff0000, v134
	v_lshlrev_b32_e32 v244, 16, v135
	v_and_b32_e32 v245, 0xffff0000, v135
	v_lshlrev_b32_e32 v246, 16, v136
	v_and_b32_e32 v247, 0xffff0000, v136
	v_lshlrev_b32_e32 v248, 16, v137
	v_and_b32_e32 v249, 0xffff0000, v137
	v_pk_mul_f32 v[242:243], v[242:243], s[86:87] op_sel_hi:[1,0]
	v_pk_mul_f32 v[244:245], v[244:245], s[86:87] op_sel_hi:[1,0]
	v_pk_mul_f32 v[246:247], v[246:247], s[86:87] op_sel_hi:[1,0]
	v_pk_mul_f32 v[248:249], v[248:249], s[86:87] op_sel_hi:[1,0]
	v_exp_f32_e32 v242, v242
	v_exp_f32_e32 v243, v243
	v_exp_f32_e32 v244, v244
	v_exp_f32_e32 v245, v245
	v_exp_f32_e32 v246, v246
	v_exp_f32_e32 v247, v247
	v_exp_f32_e32 v248, v248
	v_exp_f32_e32 v249, v249
	v_pk_add_f32 v[242:243], v[242:243], 1.0 op_sel_hi:[1,0]
	v_pk_add_f32 v[244:245], v[244:245], 1.0 op_sel_hi:[1,0]
	v_pk_add_f32 v[246:247], v[246:247], 1.0 op_sel_hi:[1,0]
	v_pk_add_f32 v[248:249], v[248:249], 1.0 op_sel_hi:[1,0]
	v_pk_mul_f32 v[216:217], v[216:217], v[242:243]
	v_pk_mul_f32 v[218:219], v[218:219], v[244:245]
	v_pk_mul_f32 v[220:221], v[220:221], v[246:247]
	v_pk_mul_f32 v[222:223], v[222:223], v[248:249]
	v_pk_mul_f32 v[126:127], v[126:127], v[216:217]
	v_pk_mul_f32 v[128:129], v[128:129], v[218:219]
	v_pk_mul_f32 v[122:123], v[122:123], v[220:221]
	v_pk_mul_f32 v[124:125], v[124:125], v[222:223]
	s_waitcnt vmcnt(12)
	v_lshlrev_b32_e32 v216, 16, v138
	v_and_b32_e32 v217, 0xffff0000, v138
	v_lshlrev_b32_e32 v218, 16, v139
	v_and_b32_e32 v219, 0xffff0000, v139
	v_lshlrev_b32_e32 v220, 16, v140
	v_and_b32_e32 v221, 0xffff0000, v140
	v_lshlrev_b32_e32 v222, 16, v141
	v_and_b32_e32 v223, 0xffff0000, v141
	v_pk_mul_f32 v[216:217], v[216:217], s[86:87] op_sel_hi:[1,0]
	v_pk_mul_f32 v[218:219], v[218:219], s[86:87] op_sel_hi:[1,0]
	v_pk_mul_f32 v[220:221], v[220:221], s[86:87] op_sel_hi:[1,0]
	v_pk_mul_f32 v[222:223], v[222:223], s[86:87] op_sel_hi:[1,0]
	v_exp_f32_e32 v216, v216
	v_exp_f32_e32 v217, v217
	v_exp_f32_e32 v218, v218
	v_exp_f32_e32 v219, v219
	v_exp_f32_e32 v220, v220
	v_exp_f32_e32 v221, v221
	v_exp_f32_e32 v222, v222
	v_exp_f32_e32 v223, v223
	v_pk_add_f32 v[216:217], v[216:217], 1.0 op_sel_hi:[1,0]
	v_pk_add_f32 v[218:219], v[218:219], 1.0 op_sel_hi:[1,0]
	v_pk_add_f32 v[220:221], v[220:221], 1.0 op_sel_hi:[1,0]
	v_pk_add_f32 v[222:223], v[222:223], 1.0 op_sel_hi:[1,0]
	v_rcp_f32_e32 v216, v216
	v_rcp_f32_e32 v217, v217
	v_rcp_f32_e32 v218, v218
	v_rcp_f32_e32 v219, v219
	v_rcp_f32_e32 v220, v220
	v_rcp_f32_e32 v221, v221
	v_rcp_f32_e32 v222, v222
	v_rcp_f32_e32 v223, v223
	v_lshlrev_b32_e32 v242, 16, v142
	v_and_b32_e32 v243, 0xffff0000, v142
	v_lshlrev_b32_e32 v244, 16, v143
	v_and_b32_e32 v245, 0xffff0000, v143
	v_lshlrev_b32_e32 v246, 16, v144
	v_and_b32_e32 v247, 0xffff0000, v144
	v_lshlrev_b32_e32 v248, 16, v145
	v_and_b32_e32 v249, 0xffff0000, v145
	v_pk_mul_f32 v[242:243], v[242:243], s[86:87] op_sel_hi:[1,0]
	v_pk_mul_f32 v[244:245], v[244:245], s[86:87] op_sel_hi:[1,0]
	v_pk_mul_f32 v[246:247], v[246:247], s[86:87] op_sel_hi:[1,0]
	v_pk_mul_f32 v[248:249], v[248:249], s[86:87] op_sel_hi:[1,0]
	v_exp_f32_e32 v242, v242
	v_exp_f32_e32 v243, v243
	v_exp_f32_e32 v244, v244
	v_exp_f32_e32 v245, v245
	v_exp_f32_e32 v246, v246
	v_exp_f32_e32 v247, v247
	v_exp_f32_e32 v248, v248
	v_exp_f32_e32 v249, v249
	v_pk_add_f32 v[242:243], v[242:243], 1.0 op_sel_hi:[1,0]
	v_pk_add_f32 v[244:245], v[244:245], 1.0 op_sel_hi:[1,0]
	v_pk_add_f32 v[246:247], v[246:247], 1.0 op_sel_hi:[1,0]
	v_pk_add_f32 v[248:249], v[248:249], 1.0 op_sel_hi:[1,0]
	v_pk_mul_f32 v[216:217], v[216:217], v[242:243]
	v_pk_mul_f32 v[218:219], v[218:219], v[244:245]
	v_pk_mul_f32 v[220:221], v[220:221], v[246:247]
	v_pk_mul_f32 v[222:223], v[222:223], v[248:249]
	v_pk_mul_f32 v[94:95], v[94:95], v[216:217]
	v_pk_mul_f32 v[96:97], v[96:97], v[218:219]
	v_pk_mul_f32 v[90:91], v[90:91], v[220:221]
	v_pk_mul_f32 v[92:93], v[92:93], v[222:223]
	s_add_u32 s28, s20, 0x340000
	s_addc_u32 s29, s21, 0
	global_load_dwordx4 v[130:133], v253, s[28:29]
	global_load_dwordx4 v[134:137], v254, s[28:29]
	global_load_dwordx4 v[138:141], v253, s[28:29] offset:256
	global_load_dwordx4 v[142:145], v254, s[28:29] offset:256
	s_waitcnt vmcnt(14)
	v_lshlrev_b32_e32 v216, 16, v146
	v_and_b32_e32 v217, 0xffff0000, v146
	v_lshlrev_b32_e32 v218, 16, v147
	v_and_b32_e32 v219, 0xffff0000, v147
	v_lshlrev_b32_e32 v220, 16, v148
	v_and_b32_e32 v221, 0xffff0000, v148
	v_lshlrev_b32_e32 v222, 16, v149
	v_and_b32_e32 v223, 0xffff0000, v149
	v_pk_mul_f32 v[216:217], v[216:217], s[86:87] op_sel_hi:[1,0]
	v_pk_mul_f32 v[218:219], v[218:219], s[86:87] op_sel_hi:[1,0]
	v_pk_mul_f32 v[220:221], v[220:221], s[86:87] op_sel_hi:[1,0]
	v_pk_mul_f32 v[222:223], v[222:223], s[86:87] op_sel_hi:[1,0]
	v_exp_f32_e32 v216, v216
	v_exp_f32_e32 v217, v217
	v_exp_f32_e32 v218, v218
	v_exp_f32_e32 v219, v219
	v_exp_f32_e32 v220, v220
	v_exp_f32_e32 v221, v221
	v_exp_f32_e32 v222, v222
	v_exp_f32_e32 v223, v223
	v_pk_add_f32 v[216:217], v[216:217], 1.0 op_sel_hi:[1,0]
	v_pk_add_f32 v[218:219], v[218:219], 1.0 op_sel_hi:[1,0]
	v_pk_add_f32 v[220:221], v[220:221], 1.0 op_sel_hi:[1,0]
	v_pk_add_f32 v[222:223], v[222:223], 1.0 op_sel_hi:[1,0]
	v_rcp_f32_e32 v216, v216
	v_rcp_f32_e32 v217, v217
	v_rcp_f32_e32 v218, v218
	v_rcp_f32_e32 v219, v219
	v_rcp_f32_e32 v220, v220
	v_rcp_f32_e32 v221, v221
	v_rcp_f32_e32 v222, v222
	v_rcp_f32_e32 v223, v223
	v_lshlrev_b32_e32 v242, 16, v150
	v_and_b32_e32 v243, 0xffff0000, v150
	v_lshlrev_b32_e32 v244, 16, v151
	v_and_b32_e32 v245, 0xffff0000, v151
	v_lshlrev_b32_e32 v246, 16, v152
	v_and_b32_e32 v247, 0xffff0000, v152
	v_lshlrev_b32_e32 v248, 16, v153
	v_and_b32_e32 v249, 0xffff0000, v153
	v_pk_mul_f32 v[242:243], v[242:243], s[86:87] op_sel_hi:[1,0]
	v_pk_mul_f32 v[244:245], v[244:245], s[86:87] op_sel_hi:[1,0]
	v_pk_mul_f32 v[246:247], v[246:247], s[86:87] op_sel_hi:[1,0]
	v_pk_mul_f32 v[248:249], v[248:249], s[86:87] op_sel_hi:[1,0]
	v_exp_f32_e32 v242, v242
	v_exp_f32_e32 v243, v243
	v_exp_f32_e32 v244, v244
	v_exp_f32_e32 v245, v245
	v_exp_f32_e32 v246, v246
	v_exp_f32_e32 v247, v247
	v_exp_f32_e32 v248, v248
	v_exp_f32_e32 v249, v249
	v_pk_add_f32 v[242:243], v[242:243], 1.0 op_sel_hi:[1,0]
	v_pk_add_f32 v[244:245], v[244:245], 1.0 op_sel_hi:[1,0]
	v_pk_add_f32 v[246:247], v[246:247], 1.0 op_sel_hi:[1,0]
	v_pk_add_f32 v[248:249], v[248:249], 1.0 op_sel_hi:[1,0]
	v_pk_mul_f32 v[216:217], v[216:217], v[242:243]
	v_pk_mul_f32 v[218:219], v[218:219], v[244:245]
	v_pk_mul_f32 v[220:221], v[220:221], v[246:247]
	v_pk_mul_f32 v[222:223], v[222:223], v[248:249]
	v_pk_mul_f32 v[118:119], v[118:119], v[216:217]
	v_pk_mul_f32 v[120:121], v[120:121], v[218:219]
	v_pk_mul_f32 v[114:115], v[114:115], v[220:221]
	v_pk_mul_f32 v[116:117], v[116:117], v[222:223]
	s_waitcnt vmcnt(12)
	v_lshlrev_b32_e32 v216, 16, v154
	v_and_b32_e32 v217, 0xffff0000, v154
	v_lshlrev_b32_e32 v218, 16, v155
	v_and_b32_e32 v219, 0xffff0000, v155
	v_lshlrev_b32_e32 v220, 16, v156
	v_and_b32_e32 v221, 0xffff0000, v156
	v_lshlrev_b32_e32 v222, 16, v157
	v_and_b32_e32 v223, 0xffff0000, v157
	v_pk_mul_f32 v[216:217], v[216:217], s[86:87] op_sel_hi:[1,0]
	v_pk_mul_f32 v[218:219], v[218:219], s[86:87] op_sel_hi:[1,0]
	v_pk_mul_f32 v[220:221], v[220:221], s[86:87] op_sel_hi:[1,0]
	v_pk_mul_f32 v[222:223], v[222:223], s[86:87] op_sel_hi:[1,0]
	v_exp_f32_e32 v216, v216
	v_exp_f32_e32 v217, v217
	v_exp_f32_e32 v218, v218
	v_exp_f32_e32 v219, v219
	v_exp_f32_e32 v220, v220
	v_exp_f32_e32 v221, v221
	v_exp_f32_e32 v222, v222
	v_exp_f32_e32 v223, v223
	v_pk_add_f32 v[216:217], v[216:217], 1.0 op_sel_hi:[1,0]
	v_pk_add_f32 v[218:219], v[218:219], 1.0 op_sel_hi:[1,0]
	v_pk_add_f32 v[220:221], v[220:221], 1.0 op_sel_hi:[1,0]
	v_pk_add_f32 v[222:223], v[222:223], 1.0 op_sel_hi:[1,0]
	v_rcp_f32_e32 v216, v216
	v_rcp_f32_e32 v217, v217
	v_rcp_f32_e32 v218, v218
	v_rcp_f32_e32 v219, v219
	v_rcp_f32_e32 v220, v220
	v_rcp_f32_e32 v221, v221
	v_rcp_f32_e32 v222, v222
	v_rcp_f32_e32 v223, v223
	v_lshlrev_b32_e32 v242, 16, v158
	v_and_b32_e32 v243, 0xffff0000, v158
	v_lshlrev_b32_e32 v244, 16, v159
	v_and_b32_e32 v245, 0xffff0000, v159
	v_lshlrev_b32_e32 v246, 16, v160
	v_and_b32_e32 v247, 0xffff0000, v160
	v_lshlrev_b32_e32 v248, 16, v161
	v_and_b32_e32 v249, 0xffff0000, v161
	v_pk_mul_f32 v[242:243], v[242:243], s[86:87] op_sel_hi:[1,0]
	v_pk_mul_f32 v[244:245], v[244:245], s[86:87] op_sel_hi:[1,0]
	v_pk_mul_f32 v[246:247], v[246:247], s[86:87] op_sel_hi:[1,0]
	v_pk_mul_f32 v[248:249], v[248:249], s[86:87] op_sel_hi:[1,0]
	v_exp_f32_e32 v242, v242
	v_exp_f32_e32 v243, v243
	v_exp_f32_e32 v244, v244
	v_exp_f32_e32 v245, v245
	v_exp_f32_e32 v246, v246
	v_exp_f32_e32 v247, v247
	v_exp_f32_e32 v248, v248
	v_exp_f32_e32 v249, v249
	v_pk_add_f32 v[242:243], v[242:243], 1.0 op_sel_hi:[1,0]
	v_pk_add_f32 v[244:245], v[244:245], 1.0 op_sel_hi:[1,0]
	v_pk_add_f32 v[246:247], v[246:247], 1.0 op_sel_hi:[1,0]
	v_pk_add_f32 v[248:249], v[248:249], 1.0 op_sel_hi:[1,0]
	v_pk_mul_f32 v[216:217], v[216:217], v[242:243]
	v_pk_mul_f32 v[218:219], v[218:219], v[244:245]
	v_pk_mul_f32 v[220:221], v[220:221], v[246:247]
	v_pk_mul_f32 v[222:223], v[222:223], v[248:249]
	v_pk_mul_f32 v[86:87], v[86:87], v[216:217]
	v_pk_mul_f32 v[88:89], v[88:89], v[218:219]
	v_pk_mul_f32 v[82:83], v[82:83], v[220:221]
	v_pk_mul_f32 v[84:85], v[84:85], v[222:223]
	s_add_u32 s28, s20, 0x3a8000
	s_addc_u32 s29, s21, 0
	global_load_dwordx4 v[146:149], v253, s[28:29]
	global_load_dwordx4 v[150:153], v254, s[28:29]
	global_load_dwordx4 v[154:157], v253, s[28:29] offset:256
	global_load_dwordx4 v[158:161], v254, s[28:29] offset:256
	s_waitcnt vmcnt(14)
	v_lshlrev_b32_e32 v216, 16, v162
	v_and_b32_e32 v217, 0xffff0000, v162
	v_lshlrev_b32_e32 v218, 16, v163
	v_and_b32_e32 v219, 0xffff0000, v163
	v_lshlrev_b32_e32 v220, 16, v164
	v_and_b32_e32 v221, 0xffff0000, v164
	v_lshlrev_b32_e32 v222, 16, v165
	v_and_b32_e32 v223, 0xffff0000, v165
	v_pk_mul_f32 v[216:217], v[216:217], s[86:87] op_sel_hi:[1,0]
	v_pk_mul_f32 v[218:219], v[218:219], s[86:87] op_sel_hi:[1,0]
	v_pk_mul_f32 v[220:221], v[220:221], s[86:87] op_sel_hi:[1,0]
	v_pk_mul_f32 v[222:223], v[222:223], s[86:87] op_sel_hi:[1,0]
	v_exp_f32_e32 v216, v216
	v_exp_f32_e32 v217, v217
	v_exp_f32_e32 v218, v218
	v_exp_f32_e32 v219, v219
	v_exp_f32_e32 v220, v220
	v_exp_f32_e32 v221, v221
	v_exp_f32_e32 v222, v222
	v_exp_f32_e32 v223, v223
	v_pk_add_f32 v[216:217], v[216:217], 1.0 op_sel_hi:[1,0]
	v_pk_add_f32 v[218:219], v[218:219], 1.0 op_sel_hi:[1,0]
	v_pk_add_f32 v[220:221], v[220:221], 1.0 op_sel_hi:[1,0]
	v_pk_add_f32 v[222:223], v[222:223], 1.0 op_sel_hi:[1,0]
	v_rcp_f32_e32 v216, v216
	v_rcp_f32_e32 v217, v217
	v_rcp_f32_e32 v218, v218
	v_rcp_f32_e32 v219, v219
	v_rcp_f32_e32 v220, v220
	v_rcp_f32_e32 v221, v221
	v_rcp_f32_e32 v222, v222
	v_rcp_f32_e32 v223, v223
	v_lshlrev_b32_e32 v242, 16, v166
	v_and_b32_e32 v243, 0xffff0000, v166
	v_lshlrev_b32_e32 v244, 16, v167
	v_and_b32_e32 v245, 0xffff0000, v167
	v_lshlrev_b32_e32 v246, 16, v168
	v_and_b32_e32 v247, 0xffff0000, v168
	v_lshlrev_b32_e32 v248, 16, v169
	v_and_b32_e32 v249, 0xffff0000, v169
	v_pk_mul_f32 v[242:243], v[242:243], s[86:87] op_sel_hi:[1,0]
	v_pk_mul_f32 v[244:245], v[244:245], s[86:87] op_sel_hi:[1,0]
	v_pk_mul_f32 v[246:247], v[246:247], s[86:87] op_sel_hi:[1,0]
	v_pk_mul_f32 v[248:249], v[248:249], s[86:87] op_sel_hi:[1,0]
	v_exp_f32_e32 v242, v242
	v_exp_f32_e32 v243, v243
	v_exp_f32_e32 v244, v244
	v_exp_f32_e32 v245, v245
	v_exp_f32_e32 v246, v246
	v_exp_f32_e32 v247, v247
	v_exp_f32_e32 v248, v248
	v_exp_f32_e32 v249, v249
	v_pk_add_f32 v[242:243], v[242:243], 1.0 op_sel_hi:[1,0]
	v_pk_add_f32 v[244:245], v[244:245], 1.0 op_sel_hi:[1,0]
	v_pk_add_f32 v[246:247], v[246:247], 1.0 op_sel_hi:[1,0]
	v_pk_add_f32 v[248:249], v[248:249], 1.0 op_sel_hi:[1,0]
	v_pk_mul_f32 v[216:217], v[216:217], v[242:243]
	v_pk_mul_f32 v[218:219], v[218:219], v[244:245]
	v_pk_mul_f32 v[220:221], v[220:221], v[246:247]
	v_pk_mul_f32 v[222:223], v[222:223], v[248:249]
	v_pk_mul_f32 v[110:111], v[110:111], v[216:217]
	v_pk_mul_f32 v[112:113], v[112:113], v[218:219]
	v_pk_mul_f32 v[106:107], v[106:107], v[220:221]
	v_pk_mul_f32 v[108:109], v[108:109], v[222:223]
	s_waitcnt vmcnt(12)
	v_lshlrev_b32_e32 v216, 16, v170
	v_and_b32_e32 v217, 0xffff0000, v170
	v_lshlrev_b32_e32 v218, 16, v171
	v_and_b32_e32 v219, 0xffff0000, v171
	v_lshlrev_b32_e32 v220, 16, v172
	v_and_b32_e32 v221, 0xffff0000, v172
	v_lshlrev_b32_e32 v222, 16, v173
	v_and_b32_e32 v223, 0xffff0000, v173
	v_pk_mul_f32 v[216:217], v[216:217], s[86:87] op_sel_hi:[1,0]
	v_pk_mul_f32 v[218:219], v[218:219], s[86:87] op_sel_hi:[1,0]
	v_pk_mul_f32 v[220:221], v[220:221], s[86:87] op_sel_hi:[1,0]
	v_pk_mul_f32 v[222:223], v[222:223], s[86:87] op_sel_hi:[1,0]
	v_exp_f32_e32 v216, v216
	v_exp_f32_e32 v217, v217
	v_exp_f32_e32 v218, v218
	v_exp_f32_e32 v219, v219
	v_exp_f32_e32 v220, v220
	v_exp_f32_e32 v221, v221
	v_exp_f32_e32 v222, v222
	v_exp_f32_e32 v223, v223
	v_pk_add_f32 v[216:217], v[216:217], 1.0 op_sel_hi:[1,0]
	v_pk_add_f32 v[218:219], v[218:219], 1.0 op_sel_hi:[1,0]
	v_pk_add_f32 v[220:221], v[220:221], 1.0 op_sel_hi:[1,0]
	v_pk_add_f32 v[222:223], v[222:223], 1.0 op_sel_hi:[1,0]
	v_rcp_f32_e32 v216, v216
	v_rcp_f32_e32 v217, v217
	v_rcp_f32_e32 v218, v218
	v_rcp_f32_e32 v219, v219
	v_rcp_f32_e32 v220, v220
	v_rcp_f32_e32 v221, v221
	v_rcp_f32_e32 v222, v222
	v_rcp_f32_e32 v223, v223
	v_lshlrev_b32_e32 v242, 16, v174
	v_and_b32_e32 v243, 0xffff0000, v174
	v_lshlrev_b32_e32 v244, 16, v175
	v_and_b32_e32 v245, 0xffff0000, v175
	v_lshlrev_b32_e32 v246, 16, v176
	v_and_b32_e32 v247, 0xffff0000, v176
	v_lshlrev_b32_e32 v248, 16, v177
	v_and_b32_e32 v249, 0xffff0000, v177
	v_pk_mul_f32 v[242:243], v[242:243], s[86:87] op_sel_hi:[1,0]
	v_pk_mul_f32 v[244:245], v[244:245], s[86:87] op_sel_hi:[1,0]
	v_pk_mul_f32 v[246:247], v[246:247], s[86:87] op_sel_hi:[1,0]
	v_pk_mul_f32 v[248:249], v[248:249], s[86:87] op_sel_hi:[1,0]
	v_exp_f32_e32 v242, v242
	v_exp_f32_e32 v243, v243
	v_exp_f32_e32 v244, v244
	v_exp_f32_e32 v245, v245
	v_exp_f32_e32 v246, v246
	v_exp_f32_e32 v247, v247
	v_exp_f32_e32 v248, v248
	v_exp_f32_e32 v249, v249
	v_pk_add_f32 v[242:243], v[242:243], 1.0 op_sel_hi:[1,0]
	v_pk_add_f32 v[244:245], v[244:245], 1.0 op_sel_hi:[1,0]
	v_pk_add_f32 v[246:247], v[246:247], 1.0 op_sel_hi:[1,0]
	v_pk_add_f32 v[248:249], v[248:249], 1.0 op_sel_hi:[1,0]
	v_pk_mul_f32 v[216:217], v[216:217], v[242:243]
	v_pk_mul_f32 v[218:219], v[218:219], v[244:245]
	v_pk_mul_f32 v[220:221], v[220:221], v[246:247]
	v_pk_mul_f32 v[222:223], v[222:223], v[248:249]
	v_pk_mul_f32 v[78:79], v[78:79], v[216:217]
	v_pk_mul_f32 v[80:81], v[80:81], v[218:219]
	v_pk_mul_f32 v[74:75], v[74:75], v[220:221]
	v_pk_mul_f32 v[76:77], v[76:77], v[222:223]
	s_add_u32 s28, s20, 0x410000
	s_addc_u32 s29, s21, 0
	global_load_dwordx4 v[162:165], v253, s[28:29]
	global_load_dwordx4 v[166:169], v254, s[28:29]
	global_load_dwordx4 v[170:173], v253, s[28:29] offset:256
	global_load_dwordx4 v[174:177], v254, s[28:29] offset:256
	s_waitcnt vmcnt(14)
	v_lshlrev_b32_e32 v216, 16, v178
	v_and_b32_e32 v217, 0xffff0000, v178
	v_lshlrev_b32_e32 v218, 16, v179
	v_and_b32_e32 v219, 0xffff0000, v179
	v_lshlrev_b32_e32 v220, 16, v180
	v_and_b32_e32 v221, 0xffff0000, v180
	v_lshlrev_b32_e32 v222, 16, v181
	v_and_b32_e32 v223, 0xffff0000, v181
	v_pk_mul_f32 v[216:217], v[216:217], s[86:87] op_sel_hi:[1,0]
	v_pk_mul_f32 v[218:219], v[218:219], s[86:87] op_sel_hi:[1,0]
	v_pk_mul_f32 v[220:221], v[220:221], s[86:87] op_sel_hi:[1,0]
	v_pk_mul_f32 v[222:223], v[222:223], s[86:87] op_sel_hi:[1,0]
	v_exp_f32_e32 v216, v216
	v_exp_f32_e32 v217, v217
	v_exp_f32_e32 v218, v218
	v_exp_f32_e32 v219, v219
	v_exp_f32_e32 v220, v220
	v_exp_f32_e32 v221, v221
	v_exp_f32_e32 v222, v222
	v_exp_f32_e32 v223, v223
	v_pk_add_f32 v[216:217], v[216:217], 1.0 op_sel_hi:[1,0]
	v_pk_add_f32 v[218:219], v[218:219], 1.0 op_sel_hi:[1,0]
	v_pk_add_f32 v[220:221], v[220:221], 1.0 op_sel_hi:[1,0]
	v_pk_add_f32 v[222:223], v[222:223], 1.0 op_sel_hi:[1,0]
	v_rcp_f32_e32 v216, v216
	v_rcp_f32_e32 v217, v217
	v_rcp_f32_e32 v218, v218
	v_rcp_f32_e32 v219, v219
	v_rcp_f32_e32 v220, v220
	v_rcp_f32_e32 v221, v221
	v_rcp_f32_e32 v222, v222
	v_rcp_f32_e32 v223, v223
	v_lshlrev_b32_e32 v242, 16, v182
	v_and_b32_e32 v243, 0xffff0000, v182
	v_lshlrev_b32_e32 v244, 16, v183
	v_and_b32_e32 v245, 0xffff0000, v183
	v_lshlrev_b32_e32 v246, 16, v184
	v_and_b32_e32 v247, 0xffff0000, v184
	v_lshlrev_b32_e32 v248, 16, v185
	v_and_b32_e32 v249, 0xffff0000, v185
	v_pk_mul_f32 v[242:243], v[242:243], s[86:87] op_sel_hi:[1,0]
	v_pk_mul_f32 v[244:245], v[244:245], s[86:87] op_sel_hi:[1,0]
	v_pk_mul_f32 v[246:247], v[246:247], s[86:87] op_sel_hi:[1,0]
	v_pk_mul_f32 v[248:249], v[248:249], s[86:87] op_sel_hi:[1,0]
	v_exp_f32_e32 v242, v242
	v_exp_f32_e32 v243, v243
	v_exp_f32_e32 v244, v244
	v_exp_f32_e32 v245, v245
	v_exp_f32_e32 v246, v246
	v_exp_f32_e32 v247, v247
	v_exp_f32_e32 v248, v248
	v_exp_f32_e32 v249, v249
	v_pk_add_f32 v[242:243], v[242:243], 1.0 op_sel_hi:[1,0]
	v_pk_add_f32 v[244:245], v[244:245], 1.0 op_sel_hi:[1,0]
	v_pk_add_f32 v[246:247], v[246:247], 1.0 op_sel_hi:[1,0]
	v_pk_add_f32 v[248:249], v[248:249], 1.0 op_sel_hi:[1,0]
	v_pk_mul_f32 v[216:217], v[216:217], v[242:243]
	v_pk_mul_f32 v[218:219], v[218:219], v[244:245]
	v_pk_mul_f32 v[220:221], v[220:221], v[246:247]
	v_pk_mul_f32 v[222:223], v[222:223], v[248:249]
	v_pk_mul_f32 v[102:103], v[102:103], v[216:217]
	v_pk_mul_f32 v[104:105], v[104:105], v[218:219]
	v_pk_mul_f32 v[98:99], v[98:99], v[220:221]
	v_pk_mul_f32 v[100:101], v[100:101], v[222:223]
	s_waitcnt vmcnt(12)
	v_lshlrev_b32_e32 v216, 16, v186
	v_and_b32_e32 v217, 0xffff0000, v186
	v_lshlrev_b32_e32 v218, 16, v187
	v_and_b32_e32 v219, 0xffff0000, v187
	v_lshlrev_b32_e32 v220, 16, v188
	v_and_b32_e32 v221, 0xffff0000, v188
	v_lshlrev_b32_e32 v222, 16, v189
	v_and_b32_e32 v223, 0xffff0000, v189
	v_pk_mul_f32 v[216:217], v[216:217], s[86:87] op_sel_hi:[1,0]
	v_pk_mul_f32 v[218:219], v[218:219], s[86:87] op_sel_hi:[1,0]
	v_pk_mul_f32 v[220:221], v[220:221], s[86:87] op_sel_hi:[1,0]
	v_pk_mul_f32 v[222:223], v[222:223], s[86:87] op_sel_hi:[1,0]
	v_exp_f32_e32 v216, v216
	v_exp_f32_e32 v217, v217
	v_exp_f32_e32 v218, v218
	v_exp_f32_e32 v219, v219
	v_exp_f32_e32 v220, v220
	v_exp_f32_e32 v221, v221
	v_exp_f32_e32 v222, v222
	v_exp_f32_e32 v223, v223
	v_pk_add_f32 v[216:217], v[216:217], 1.0 op_sel_hi:[1,0]
	v_pk_add_f32 v[218:219], v[218:219], 1.0 op_sel_hi:[1,0]
	v_pk_add_f32 v[220:221], v[220:221], 1.0 op_sel_hi:[1,0]
	v_pk_add_f32 v[222:223], v[222:223], 1.0 op_sel_hi:[1,0]
	v_rcp_f32_e32 v216, v216
	v_rcp_f32_e32 v217, v217
	v_rcp_f32_e32 v218, v218
	v_rcp_f32_e32 v219, v219
	v_rcp_f32_e32 v220, v220
	v_rcp_f32_e32 v221, v221
	v_rcp_f32_e32 v222, v222
	v_rcp_f32_e32 v223, v223
	v_lshlrev_b32_e32 v242, 16, v190
	v_and_b32_e32 v243, 0xffff0000, v190
	v_lshlrev_b32_e32 v244, 16, v191
	v_and_b32_e32 v245, 0xffff0000, v191
	v_lshlrev_b32_e32 v246, 16, v192
	v_and_b32_e32 v247, 0xffff0000, v192
	v_lshlrev_b32_e32 v248, 16, v193
	v_and_b32_e32 v249, 0xffff0000, v193
	v_pk_mul_f32 v[242:243], v[242:243], s[86:87] op_sel_hi:[1,0]
	v_pk_mul_f32 v[244:245], v[244:245], s[86:87] op_sel_hi:[1,0]
	v_pk_mul_f32 v[246:247], v[246:247], s[86:87] op_sel_hi:[1,0]
	v_pk_mul_f32 v[248:249], v[248:249], s[86:87] op_sel_hi:[1,0]
	v_exp_f32_e32 v242, v242
	v_exp_f32_e32 v243, v243
	v_exp_f32_e32 v244, v244
	v_exp_f32_e32 v245, v245
	v_exp_f32_e32 v246, v246
	v_exp_f32_e32 v247, v247
	v_exp_f32_e32 v248, v248
	v_exp_f32_e32 v249, v249
	v_pk_add_f32 v[242:243], v[242:243], 1.0 op_sel_hi:[1,0]
	v_pk_add_f32 v[244:245], v[244:245], 1.0 op_sel_hi:[1,0]
	v_pk_add_f32 v[246:247], v[246:247], 1.0 op_sel_hi:[1,0]
	v_pk_add_f32 v[248:249], v[248:249], 1.0 op_sel_hi:[1,0]
	v_pk_mul_f32 v[216:217], v[216:217], v[242:243]
	v_pk_mul_f32 v[218:219], v[218:219], v[244:245]
	v_pk_mul_f32 v[220:221], v[220:221], v[246:247]
	v_pk_mul_f32 v[222:223], v[222:223], v[248:249]
	v_pk_mul_f32 v[70:71], v[70:71], v[216:217]
	v_pk_mul_f32 v[72:73], v[72:73], v[218:219]
	v_pk_mul_f32 v[66:67], v[66:67], v[220:221]
	v_pk_mul_f32 v[68:69], v[68:69], v[222:223]
	s_add_u32 s28, s20, 0x478000
	s_addc_u32 s29, s21, 0
	global_load_dwordx4 v[178:181], v253, s[28:29]
	global_load_dwordx4 v[182:185], v254, s[28:29]
	global_load_dwordx4 v[186:189], v253, s[28:29] offset:256
	global_load_dwordx4 v[190:193], v254, s[28:29] offset:256
	s_waitcnt vmcnt(14)
	v_lshlrev_b32_e32 v216, 16, v130
	v_and_b32_e32 v217, 0xffff0000, v130
	v_lshlrev_b32_e32 v218, 16, v131
	v_and_b32_e32 v219, 0xffff0000, v131
	v_lshlrev_b32_e32 v220, 16, v132
	v_and_b32_e32 v221, 0xffff0000, v132
	v_lshlrev_b32_e32 v222, 16, v133
	v_and_b32_e32 v223, 0xffff0000, v133
	v_pk_mul_f32 v[216:217], v[216:217], s[86:87] op_sel_hi:[1,0]
	v_pk_mul_f32 v[218:219], v[218:219], s[86:87] op_sel_hi:[1,0]
	v_pk_mul_f32 v[220:221], v[220:221], s[86:87] op_sel_hi:[1,0]
	v_pk_mul_f32 v[222:223], v[222:223], s[86:87] op_sel_hi:[1,0]
	v_exp_f32_e32 v216, v216
	v_exp_f32_e32 v217, v217
	v_exp_f32_e32 v218, v218
	v_exp_f32_e32 v219, v219
	v_exp_f32_e32 v220, v220
	v_exp_f32_e32 v221, v221
	v_exp_f32_e32 v222, v222
	v_exp_f32_e32 v223, v223
	v_pk_add_f32 v[216:217], v[216:217], 1.0 op_sel_hi:[1,0]
	v_pk_add_f32 v[218:219], v[218:219], 1.0 op_sel_hi:[1,0]
	v_pk_add_f32 v[220:221], v[220:221], 1.0 op_sel_hi:[1,0]
	v_pk_add_f32 v[222:223], v[222:223], 1.0 op_sel_hi:[1,0]
	v_rcp_f32_e32 v216, v216
	v_rcp_f32_e32 v217, v217
	v_rcp_f32_e32 v218, v218
	v_rcp_f32_e32 v219, v219
	v_rcp_f32_e32 v220, v220
	v_rcp_f32_e32 v221, v221
	v_rcp_f32_e32 v222, v222
	v_rcp_f32_e32 v223, v223
	v_lshlrev_b32_e32 v242, 16, v134
	v_and_b32_e32 v243, 0xffff0000, v134
	v_lshlrev_b32_e32 v244, 16, v135
	v_and_b32_e32 v245, 0xffff0000, v135
	v_lshlrev_b32_e32 v246, 16, v136
	v_and_b32_e32 v247, 0xffff0000, v136
	v_lshlrev_b32_e32 v248, 16, v137
	v_and_b32_e32 v249, 0xffff0000, v137
	v_pk_mul_f32 v[242:243], v[242:243], s[86:87] op_sel_hi:[1,0]
	v_pk_mul_f32 v[244:245], v[244:245], s[86:87] op_sel_hi:[1,0]
	v_pk_mul_f32 v[246:247], v[246:247], s[86:87] op_sel_hi:[1,0]
	v_pk_mul_f32 v[248:249], v[248:249], s[86:87] op_sel_hi:[1,0]
	v_exp_f32_e32 v242, v242
	v_exp_f32_e32 v243, v243
	v_exp_f32_e32 v244, v244
	v_exp_f32_e32 v245, v245
	v_exp_f32_e32 v246, v246
	v_exp_f32_e32 v247, v247
	v_exp_f32_e32 v248, v248
	v_exp_f32_e32 v249, v249
	v_pk_add_f32 v[242:243], v[242:243], 1.0 op_sel_hi:[1,0]
	v_pk_add_f32 v[244:245], v[244:245], 1.0 op_sel_hi:[1,0]
	v_pk_add_f32 v[246:247], v[246:247], 1.0 op_sel_hi:[1,0]
	v_pk_add_f32 v[248:249], v[248:249], 1.0 op_sel_hi:[1,0]
	v_pk_mul_f32 v[216:217], v[216:217], v[242:243]
	v_pk_mul_f32 v[218:219], v[218:219], v[244:245]
	v_pk_mul_f32 v[220:221], v[220:221], v[246:247]
	v_pk_mul_f32 v[222:223], v[222:223], v[248:249]
	v_pk_mul_f32 v[62:63], v[62:63], v[216:217]
	v_pk_mul_f32 v[64:65], v[64:65], v[218:219]
	v_pk_mul_f32 v[58:59], v[58:59], v[220:221]
	v_pk_mul_f32 v[60:61], v[60:61], v[222:223]
	s_waitcnt vmcnt(12)
	v_lshlrev_b32_e32 v216, 16, v138
	v_and_b32_e32 v217, 0xffff0000, v138
	v_lshlrev_b32_e32 v218, 16, v139
	v_and_b32_e32 v219, 0xffff0000, v139
	v_lshlrev_b32_e32 v220, 16, v140
	v_and_b32_e32 v221, 0xffff0000, v140
	v_lshlrev_b32_e32 v222, 16, v141
	v_and_b32_e32 v223, 0xffff0000, v141
	v_pk_mul_f32 v[216:217], v[216:217], s[86:87] op_sel_hi:[1,0]
	v_pk_mul_f32 v[218:219], v[218:219], s[86:87] op_sel_hi:[1,0]
	v_pk_mul_f32 v[220:221], v[220:221], s[86:87] op_sel_hi:[1,0]
	v_pk_mul_f32 v[222:223], v[222:223], s[86:87] op_sel_hi:[1,0]
	v_exp_f32_e32 v216, v216
	v_exp_f32_e32 v217, v217
	v_exp_f32_e32 v218, v218
	v_exp_f32_e32 v219, v219
	v_exp_f32_e32 v220, v220
	v_exp_f32_e32 v221, v221
	v_exp_f32_e32 v222, v222
	v_exp_f32_e32 v223, v223
	v_pk_add_f32 v[216:217], v[216:217], 1.0 op_sel_hi:[1,0]
	v_pk_add_f32 v[218:219], v[218:219], 1.0 op_sel_hi:[1,0]
	v_pk_add_f32 v[220:221], v[220:221], 1.0 op_sel_hi:[1,0]
	v_pk_add_f32 v[222:223], v[222:223], 1.0 op_sel_hi:[1,0]
	v_rcp_f32_e32 v216, v216
	v_rcp_f32_e32 v217, v217
	v_rcp_f32_e32 v218, v218
	v_rcp_f32_e32 v219, v219
	v_rcp_f32_e32 v220, v220
	v_rcp_f32_e32 v221, v221
	v_rcp_f32_e32 v222, v222
	v_rcp_f32_e32 v223, v223
	v_lshlrev_b32_e32 v242, 16, v142
	v_and_b32_e32 v243, 0xffff0000, v142
	v_lshlrev_b32_e32 v244, 16, v143
	v_and_b32_e32 v245, 0xffff0000, v143
	v_lshlrev_b32_e32 v246, 16, v144
	v_and_b32_e32 v247, 0xffff0000, v144
	v_lshlrev_b32_e32 v248, 16, v145
	v_and_b32_e32 v249, 0xffff0000, v145
	v_pk_mul_f32 v[242:243], v[242:243], s[86:87] op_sel_hi:[1,0]
	v_pk_mul_f32 v[244:245], v[244:245], s[86:87] op_sel_hi:[1,0]
	v_pk_mul_f32 v[246:247], v[246:247], s[86:87] op_sel_hi:[1,0]
	v_pk_mul_f32 v[248:249], v[248:249], s[86:87] op_sel_hi:[1,0]
	v_exp_f32_e32 v242, v242
	v_exp_f32_e32 v243, v243
	v_exp_f32_e32 v244, v244
	v_exp_f32_e32 v245, v245
	v_exp_f32_e32 v246, v246
	v_exp_f32_e32 v247, v247
	v_exp_f32_e32 v248, v248
	v_exp_f32_e32 v249, v249
	v_pk_add_f32 v[242:243], v[242:243], 1.0 op_sel_hi:[1,0]
	v_pk_add_f32 v[244:245], v[244:245], 1.0 op_sel_hi:[1,0]
	v_pk_add_f32 v[246:247], v[246:247], 1.0 op_sel_hi:[1,0]
	v_pk_add_f32 v[248:249], v[248:249], 1.0 op_sel_hi:[1,0]
	v_pk_mul_f32 v[216:217], v[216:217], v[242:243]
	v_pk_mul_f32 v[218:219], v[218:219], v[244:245]
	v_pk_mul_f32 v[220:221], v[220:221], v[246:247]
	v_pk_mul_f32 v[222:223], v[222:223], v[248:249]
	v_pk_mul_f32 v[30:31], v[30:31], v[216:217]
	v_pk_mul_f32 v[32:33], v[32:33], v[218:219]
	v_pk_mul_f32 v[26:27], v[26:27], v[220:221]
	v_pk_mul_f32 v[28:29], v[28:29], v[222:223]
	s_waitcnt vmcnt(10)
	v_lshlrev_b32_e32 v216, 16, v146
	v_and_b32_e32 v217, 0xffff0000, v146
	v_lshlrev_b32_e32 v218, 16, v147
	v_and_b32_e32 v219, 0xffff0000, v147
	v_lshlrev_b32_e32 v220, 16, v148
	v_and_b32_e32 v221, 0xffff0000, v148
	v_lshlrev_b32_e32 v222, 16, v149
	v_and_b32_e32 v223, 0xffff0000, v149
	v_pk_mul_f32 v[216:217], v[216:217], s[86:87] op_sel_hi:[1,0]
	v_pk_mul_f32 v[218:219], v[218:219], s[86:87] op_sel_hi:[1,0]
	v_pk_mul_f32 v[220:221], v[220:221], s[86:87] op_sel_hi:[1,0]
	v_pk_mul_f32 v[222:223], v[222:223], s[86:87] op_sel_hi:[1,0]
	v_exp_f32_e32 v216, v216
	v_exp_f32_e32 v217, v217
	v_exp_f32_e32 v218, v218
	v_exp_f32_e32 v219, v219
	v_exp_f32_e32 v220, v220
	v_exp_f32_e32 v221, v221
	v_exp_f32_e32 v222, v222
	v_exp_f32_e32 v223, v223
	v_pk_add_f32 v[216:217], v[216:217], 1.0 op_sel_hi:[1,0]
	v_pk_add_f32 v[218:219], v[218:219], 1.0 op_sel_hi:[1,0]
	v_pk_add_f32 v[220:221], v[220:221], 1.0 op_sel_hi:[1,0]
	v_pk_add_f32 v[222:223], v[222:223], 1.0 op_sel_hi:[1,0]
	v_rcp_f32_e32 v216, v216
	v_rcp_f32_e32 v217, v217
	v_rcp_f32_e32 v218, v218
	v_rcp_f32_e32 v219, v219
	v_rcp_f32_e32 v220, v220
	v_rcp_f32_e32 v221, v221
	v_rcp_f32_e32 v222, v222
	v_rcp_f32_e32 v223, v223
	v_lshlrev_b32_e32 v242, 16, v150
	v_and_b32_e32 v243, 0xffff0000, v150
	v_lshlrev_b32_e32 v244, 16, v151
	v_and_b32_e32 v245, 0xffff0000, v151
	v_lshlrev_b32_e32 v246, 16, v152
	v_and_b32_e32 v247, 0xffff0000, v152
	v_lshlrev_b32_e32 v248, 16, v153
	v_and_b32_e32 v249, 0xffff0000, v153
	v_pk_mul_f32 v[242:243], v[242:243], s[86:87] op_sel_hi:[1,0]
	v_pk_mul_f32 v[244:245], v[244:245], s[86:87] op_sel_hi:[1,0]
	v_pk_mul_f32 v[246:247], v[246:247], s[86:87] op_sel_hi:[1,0]
	v_pk_mul_f32 v[248:249], v[248:249], s[86:87] op_sel_hi:[1,0]
	v_exp_f32_e32 v242, v242
	v_exp_f32_e32 v243, v243
	v_exp_f32_e32 v244, v244
	v_exp_f32_e32 v245, v245
	v_exp_f32_e32 v246, v246
	v_exp_f32_e32 v247, v247
	v_exp_f32_e32 v248, v248
	v_exp_f32_e32 v249, v249
	v_pk_add_f32 v[242:243], v[242:243], 1.0 op_sel_hi:[1,0]
	v_pk_add_f32 v[244:245], v[244:245], 1.0 op_sel_hi:[1,0]
	v_pk_add_f32 v[246:247], v[246:247], 1.0 op_sel_hi:[1,0]
	v_pk_add_f32 v[248:249], v[248:249], 1.0 op_sel_hi:[1,0]
	v_pk_mul_f32 v[216:217], v[216:217], v[242:243]
	v_pk_mul_f32 v[218:219], v[218:219], v[244:245]
	v_pk_mul_f32 v[220:221], v[220:221], v[246:247]
	v_pk_mul_f32 v[222:223], v[222:223], v[248:249]
	v_pk_mul_f32 v[54:55], v[54:55], v[216:217]
	v_pk_mul_f32 v[56:57], v[56:57], v[218:219]
	v_pk_mul_f32 v[50:51], v[50:51], v[220:221]
	v_pk_mul_f32 v[52:53], v[52:53], v[222:223]
	s_waitcnt vmcnt(8)
	v_lshlrev_b32_e32 v216, 16, v154
	v_and_b32_e32 v217, 0xffff0000, v154
	v_lshlrev_b32_e32 v218, 16, v155
	v_and_b32_e32 v219, 0xffff0000, v155
	v_lshlrev_b32_e32 v220, 16, v156
	v_and_b32_e32 v221, 0xffff0000, v156
	v_lshlrev_b32_e32 v222, 16, v157
	v_and_b32_e32 v223, 0xffff0000, v157
	v_pk_mul_f32 v[216:217], v[216:217], s[86:87] op_sel_hi:[1,0]
	v_pk_mul_f32 v[218:219], v[218:219], s[86:87] op_sel_hi:[1,0]
	v_pk_mul_f32 v[220:221], v[220:221], s[86:87] op_sel_hi:[1,0]
	v_pk_mul_f32 v[222:223], v[222:223], s[86:87] op_sel_hi:[1,0]
	v_exp_f32_e32 v216, v216
	v_exp_f32_e32 v217, v217
	v_exp_f32_e32 v218, v218
	v_exp_f32_e32 v219, v219
	v_exp_f32_e32 v220, v220
	v_exp_f32_e32 v221, v221
	v_exp_f32_e32 v222, v222
	v_exp_f32_e32 v223, v223
	v_pk_add_f32 v[216:217], v[216:217], 1.0 op_sel_hi:[1,0]
	v_pk_add_f32 v[218:219], v[218:219], 1.0 op_sel_hi:[1,0]
	v_pk_add_f32 v[220:221], v[220:221], 1.0 op_sel_hi:[1,0]
	v_pk_add_f32 v[222:223], v[222:223], 1.0 op_sel_hi:[1,0]
	v_rcp_f32_e32 v216, v216
	v_rcp_f32_e32 v217, v217
	v_rcp_f32_e32 v218, v218
	v_rcp_f32_e32 v219, v219
	v_rcp_f32_e32 v220, v220
	v_rcp_f32_e32 v221, v221
	v_rcp_f32_e32 v222, v222
	v_rcp_f32_e32 v223, v223
	v_lshlrev_b32_e32 v242, 16, v158
	v_and_b32_e32 v243, 0xffff0000, v158
	v_lshlrev_b32_e32 v244, 16, v159
	v_and_b32_e32 v245, 0xffff0000, v159
	v_lshlrev_b32_e32 v246, 16, v160
	v_and_b32_e32 v247, 0xffff0000, v160
	v_lshlrev_b32_e32 v248, 16, v161
	v_and_b32_e32 v249, 0xffff0000, v161
	v_pk_mul_f32 v[242:243], v[242:243], s[86:87] op_sel_hi:[1,0]
	v_pk_mul_f32 v[244:245], v[244:245], s[86:87] op_sel_hi:[1,0]
	v_pk_mul_f32 v[246:247], v[246:247], s[86:87] op_sel_hi:[1,0]
	v_pk_mul_f32 v[248:249], v[248:249], s[86:87] op_sel_hi:[1,0]
	v_exp_f32_e32 v242, v242
	v_exp_f32_e32 v243, v243
	v_exp_f32_e32 v244, v244
	v_exp_f32_e32 v245, v245
	v_exp_f32_e32 v246, v246
	v_exp_f32_e32 v247, v247
	v_exp_f32_e32 v248, v248
	v_exp_f32_e32 v249, v249
	v_pk_add_f32 v[242:243], v[242:243], 1.0 op_sel_hi:[1,0]
	v_pk_add_f32 v[244:245], v[244:245], 1.0 op_sel_hi:[1,0]
	v_pk_add_f32 v[246:247], v[246:247], 1.0 op_sel_hi:[1,0]
	v_pk_add_f32 v[248:249], v[248:249], 1.0 op_sel_hi:[1,0]
	v_pk_mul_f32 v[216:217], v[216:217], v[242:243]
	v_pk_mul_f32 v[218:219], v[218:219], v[244:245]
	v_pk_mul_f32 v[220:221], v[220:221], v[246:247]
	v_pk_mul_f32 v[222:223], v[222:223], v[248:249]
	v_pk_mul_f32 v[22:23], v[22:23], v[216:217]
	v_pk_mul_f32 v[24:25], v[24:25], v[218:219]
	v_pk_mul_f32 v[18:19], v[18:19], v[220:221]
	v_pk_mul_f32 v[20:21], v[20:21], v[222:223]
	s_waitcnt vmcnt(6)
	v_lshlrev_b32_e32 v216, 16, v162
	v_and_b32_e32 v217, 0xffff0000, v162
	v_lshlrev_b32_e32 v218, 16, v163
	v_and_b32_e32 v219, 0xffff0000, v163
	v_lshlrev_b32_e32 v220, 16, v164
	v_and_b32_e32 v221, 0xffff0000, v164
	v_lshlrev_b32_e32 v222, 16, v165
	v_and_b32_e32 v223, 0xffff0000, v165
	v_pk_mul_f32 v[216:217], v[216:217], s[86:87] op_sel_hi:[1,0]
	v_pk_mul_f32 v[218:219], v[218:219], s[86:87] op_sel_hi:[1,0]
	v_pk_mul_f32 v[220:221], v[220:221], s[86:87] op_sel_hi:[1,0]
	v_pk_mul_f32 v[222:223], v[222:223], s[86:87] op_sel_hi:[1,0]
	v_exp_f32_e32 v216, v216
	v_exp_f32_e32 v217, v217
	v_exp_f32_e32 v218, v218
	v_exp_f32_e32 v219, v219
	v_exp_f32_e32 v220, v220
	v_exp_f32_e32 v221, v221
	v_exp_f32_e32 v222, v222
	v_exp_f32_e32 v223, v223
	v_pk_add_f32 v[216:217], v[216:217], 1.0 op_sel_hi:[1,0]
	v_pk_add_f32 v[218:219], v[218:219], 1.0 op_sel_hi:[1,0]
	v_pk_add_f32 v[220:221], v[220:221], 1.0 op_sel_hi:[1,0]
	v_pk_add_f32 v[222:223], v[222:223], 1.0 op_sel_hi:[1,0]
	v_rcp_f32_e32 v216, v216
	v_rcp_f32_e32 v217, v217
	v_rcp_f32_e32 v218, v218
	v_rcp_f32_e32 v219, v219
	v_rcp_f32_e32 v220, v220
	v_rcp_f32_e32 v221, v221
	v_rcp_f32_e32 v222, v222
	v_rcp_f32_e32 v223, v223
	v_lshlrev_b32_e32 v242, 16, v166
	v_and_b32_e32 v243, 0xffff0000, v166
	v_lshlrev_b32_e32 v244, 16, v167
	v_and_b32_e32 v245, 0xffff0000, v167
	v_lshlrev_b32_e32 v246, 16, v168
	v_and_b32_e32 v247, 0xffff0000, v168
	v_lshlrev_b32_e32 v248, 16, v169
	v_and_b32_e32 v249, 0xffff0000, v169
	v_pk_mul_f32 v[242:243], v[242:243], s[86:87] op_sel_hi:[1,0]
	v_pk_mul_f32 v[244:245], v[244:245], s[86:87] op_sel_hi:[1,0]
	v_pk_mul_f32 v[246:247], v[246:247], s[86:87] op_sel_hi:[1,0]
	v_pk_mul_f32 v[248:249], v[248:249], s[86:87] op_sel_hi:[1,0]
	v_exp_f32_e32 v242, v242
	v_exp_f32_e32 v243, v243
	v_exp_f32_e32 v244, v244
	v_exp_f32_e32 v245, v245
	v_exp_f32_e32 v246, v246
	v_exp_f32_e32 v247, v247
	v_exp_f32_e32 v248, v248
	v_exp_f32_e32 v249, v249
	v_pk_add_f32 v[242:243], v[242:243], 1.0 op_sel_hi:[1,0]
	v_pk_add_f32 v[244:245], v[244:245], 1.0 op_sel_hi:[1,0]
	v_pk_add_f32 v[246:247], v[246:247], 1.0 op_sel_hi:[1,0]
	v_pk_add_f32 v[248:249], v[248:249], 1.0 op_sel_hi:[1,0]
	v_pk_mul_f32 v[216:217], v[216:217], v[242:243]
	v_pk_mul_f32 v[218:219], v[218:219], v[244:245]
	v_pk_mul_f32 v[220:221], v[220:221], v[246:247]
	v_pk_mul_f32 v[222:223], v[222:223], v[248:249]
	v_pk_mul_f32 v[46:47], v[46:47], v[216:217]
	v_pk_mul_f32 v[48:49], v[48:49], v[218:219]
	v_pk_mul_f32 v[42:43], v[42:43], v[220:221]
	v_pk_mul_f32 v[44:45], v[44:45], v[222:223]
	s_waitcnt vmcnt(4)
	v_lshlrev_b32_e32 v216, 16, v170
	v_and_b32_e32 v217, 0xffff0000, v170
	v_lshlrev_b32_e32 v218, 16, v171
	v_and_b32_e32 v219, 0xffff0000, v171
	v_lshlrev_b32_e32 v220, 16, v172
	v_and_b32_e32 v221, 0xffff0000, v172
	v_lshlrev_b32_e32 v222, 16, v173
	v_and_b32_e32 v223, 0xffff0000, v173
	v_pk_mul_f32 v[216:217], v[216:217], s[86:87] op_sel_hi:[1,0]
	v_pk_mul_f32 v[218:219], v[218:219], s[86:87] op_sel_hi:[1,0]
	v_pk_mul_f32 v[220:221], v[220:221], s[86:87] op_sel_hi:[1,0]
	v_pk_mul_f32 v[222:223], v[222:223], s[86:87] op_sel_hi:[1,0]
	v_exp_f32_e32 v216, v216
	v_exp_f32_e32 v217, v217
	v_exp_f32_e32 v218, v218
	v_exp_f32_e32 v219, v219
	v_exp_f32_e32 v220, v220
	v_exp_f32_e32 v221, v221
	v_exp_f32_e32 v222, v222
	v_exp_f32_e32 v223, v223
	v_pk_add_f32 v[216:217], v[216:217], 1.0 op_sel_hi:[1,0]
	v_pk_add_f32 v[218:219], v[218:219], 1.0 op_sel_hi:[1,0]
	v_pk_add_f32 v[220:221], v[220:221], 1.0 op_sel_hi:[1,0]
	v_pk_add_f32 v[222:223], v[222:223], 1.0 op_sel_hi:[1,0]
	v_rcp_f32_e32 v216, v216
	v_rcp_f32_e32 v217, v217
	v_rcp_f32_e32 v218, v218
	v_rcp_f32_e32 v219, v219
	v_rcp_f32_e32 v220, v220
	v_rcp_f32_e32 v221, v221
	v_rcp_f32_e32 v222, v222
	v_rcp_f32_e32 v223, v223
	v_lshlrev_b32_e32 v242, 16, v174
	v_and_b32_e32 v243, 0xffff0000, v174
	v_lshlrev_b32_e32 v244, 16, v175
	v_and_b32_e32 v245, 0xffff0000, v175
	v_lshlrev_b32_e32 v246, 16, v176
	v_and_b32_e32 v247, 0xffff0000, v176
	v_lshlrev_b32_e32 v248, 16, v177
	v_and_b32_e32 v249, 0xffff0000, v177
	v_pk_mul_f32 v[242:243], v[242:243], s[86:87] op_sel_hi:[1,0]
	v_pk_mul_f32 v[244:245], v[244:245], s[86:87] op_sel_hi:[1,0]
	v_pk_mul_f32 v[246:247], v[246:247], s[86:87] op_sel_hi:[1,0]
	v_pk_mul_f32 v[248:249], v[248:249], s[86:87] op_sel_hi:[1,0]
	v_exp_f32_e32 v242, v242
	v_exp_f32_e32 v243, v243
	v_exp_f32_e32 v244, v244
	v_exp_f32_e32 v245, v245
	v_exp_f32_e32 v246, v246
	v_exp_f32_e32 v247, v247
	v_exp_f32_e32 v248, v248
	v_exp_f32_e32 v249, v249
	v_pk_add_f32 v[242:243], v[242:243], 1.0 op_sel_hi:[1,0]
	v_pk_add_f32 v[244:245], v[244:245], 1.0 op_sel_hi:[1,0]
	v_pk_add_f32 v[246:247], v[246:247], 1.0 op_sel_hi:[1,0]
	v_pk_add_f32 v[248:249], v[248:249], 1.0 op_sel_hi:[1,0]
	v_pk_mul_f32 v[216:217], v[216:217], v[242:243]
	v_pk_mul_f32 v[218:219], v[218:219], v[244:245]
	v_pk_mul_f32 v[220:221], v[220:221], v[246:247]
	v_pk_mul_f32 v[222:223], v[222:223], v[248:249]
	v_pk_mul_f32 v[14:15], v[14:15], v[216:217]
	v_pk_mul_f32 v[16:17], v[16:17], v[218:219]
	v_pk_mul_f32 v[10:11], v[10:11], v[220:221]
	v_pk_mul_f32 v[12:13], v[12:13], v[222:223]
	s_waitcnt vmcnt(2)
	v_lshlrev_b32_e32 v216, 16, v178
	v_and_b32_e32 v217, 0xffff0000, v178
	v_lshlrev_b32_e32 v218, 16, v179
	v_and_b32_e32 v219, 0xffff0000, v179
	v_lshlrev_b32_e32 v220, 16, v180
	v_and_b32_e32 v221, 0xffff0000, v180
	v_lshlrev_b32_e32 v222, 16, v181
	v_and_b32_e32 v223, 0xffff0000, v181
	v_pk_mul_f32 v[216:217], v[216:217], s[86:87] op_sel_hi:[1,0]
	v_pk_mul_f32 v[218:219], v[218:219], s[86:87] op_sel_hi:[1,0]
	v_pk_mul_f32 v[220:221], v[220:221], s[86:87] op_sel_hi:[1,0]
	v_pk_mul_f32 v[222:223], v[222:223], s[86:87] op_sel_hi:[1,0]
	v_exp_f32_e32 v216, v216
	v_exp_f32_e32 v217, v217
	v_exp_f32_e32 v218, v218
	v_exp_f32_e32 v219, v219
	v_exp_f32_e32 v220, v220
	v_exp_f32_e32 v221, v221
	v_exp_f32_e32 v222, v222
	v_exp_f32_e32 v223, v223
	v_pk_add_f32 v[216:217], v[216:217], 1.0 op_sel_hi:[1,0]
	v_pk_add_f32 v[218:219], v[218:219], 1.0 op_sel_hi:[1,0]
	v_pk_add_f32 v[220:221], v[220:221], 1.0 op_sel_hi:[1,0]
	v_pk_add_f32 v[222:223], v[222:223], 1.0 op_sel_hi:[1,0]
	v_rcp_f32_e32 v216, v216
	v_rcp_f32_e32 v217, v217
	v_rcp_f32_e32 v218, v218
	v_rcp_f32_e32 v219, v219
	v_rcp_f32_e32 v220, v220
	v_rcp_f32_e32 v221, v221
	v_rcp_f32_e32 v222, v222
	v_rcp_f32_e32 v223, v223
	v_lshlrev_b32_e32 v242, 16, v182
	v_and_b32_e32 v243, 0xffff0000, v182
	v_lshlrev_b32_e32 v244, 16, v183
	v_and_b32_e32 v245, 0xffff0000, v183
	v_lshlrev_b32_e32 v246, 16, v184
	v_and_b32_e32 v247, 0xffff0000, v184
	v_lshlrev_b32_e32 v248, 16, v185
	v_and_b32_e32 v249, 0xffff0000, v185
	v_pk_mul_f32 v[242:243], v[242:243], s[86:87] op_sel_hi:[1,0]
	v_pk_mul_f32 v[244:245], v[244:245], s[86:87] op_sel_hi:[1,0]
	v_pk_mul_f32 v[246:247], v[246:247], s[86:87] op_sel_hi:[1,0]
	v_pk_mul_f32 v[248:249], v[248:249], s[86:87] op_sel_hi:[1,0]
	v_exp_f32_e32 v242, v242
	v_exp_f32_e32 v243, v243
	v_exp_f32_e32 v244, v244
	v_exp_f32_e32 v245, v245
	v_exp_f32_e32 v246, v246
	v_exp_f32_e32 v247, v247
	v_exp_f32_e32 v248, v248
	v_exp_f32_e32 v249, v249
	v_pk_add_f32 v[242:243], v[242:243], 1.0 op_sel_hi:[1,0]
	v_pk_add_f32 v[244:245], v[244:245], 1.0 op_sel_hi:[1,0]
	v_pk_add_f32 v[246:247], v[246:247], 1.0 op_sel_hi:[1,0]
	v_pk_add_f32 v[248:249], v[248:249], 1.0 op_sel_hi:[1,0]
	v_pk_mul_f32 v[216:217], v[216:217], v[242:243]
	v_pk_mul_f32 v[218:219], v[218:219], v[244:245]
	v_pk_mul_f32 v[220:221], v[220:221], v[246:247]
	v_pk_mul_f32 v[222:223], v[222:223], v[248:249]
	v_pk_mul_f32 v[38:39], v[38:39], v[216:217]
	v_pk_mul_f32 v[40:41], v[40:41], v[218:219]
	v_pk_mul_f32 v[34:35], v[34:35], v[220:221]
	v_pk_mul_f32 v[36:37], v[36:37], v[222:223]
	s_waitcnt vmcnt(0)
	v_lshlrev_b32_e32 v216, 16, v186
	v_and_b32_e32 v217, 0xffff0000, v186
	v_lshlrev_b32_e32 v218, 16, v187
	v_and_b32_e32 v219, 0xffff0000, v187
	v_lshlrev_b32_e32 v220, 16, v188
	v_and_b32_e32 v221, 0xffff0000, v188
	v_lshlrev_b32_e32 v222, 16, v189
	v_and_b32_e32 v223, 0xffff0000, v189
	v_pk_mul_f32 v[216:217], v[216:217], s[86:87] op_sel_hi:[1,0]
	v_pk_mul_f32 v[218:219], v[218:219], s[86:87] op_sel_hi:[1,0]
	v_pk_mul_f32 v[220:221], v[220:221], s[86:87] op_sel_hi:[1,0]
	v_pk_mul_f32 v[222:223], v[222:223], s[86:87] op_sel_hi:[1,0]
	v_exp_f32_e32 v216, v216
	v_exp_f32_e32 v217, v217
	v_exp_f32_e32 v218, v218
	v_exp_f32_e32 v219, v219
	v_exp_f32_e32 v220, v220
	v_exp_f32_e32 v221, v221
	v_exp_f32_e32 v222, v222
	v_exp_f32_e32 v223, v223
	v_pk_add_f32 v[216:217], v[216:217], 1.0 op_sel_hi:[1,0]
	v_pk_add_f32 v[218:219], v[218:219], 1.0 op_sel_hi:[1,0]
	v_pk_add_f32 v[220:221], v[220:221], 1.0 op_sel_hi:[1,0]
	v_pk_add_f32 v[222:223], v[222:223], 1.0 op_sel_hi:[1,0]
	v_rcp_f32_e32 v216, v216
	v_rcp_f32_e32 v217, v217
	v_rcp_f32_e32 v218, v218
	v_rcp_f32_e32 v219, v219
	v_rcp_f32_e32 v220, v220
	v_rcp_f32_e32 v221, v221
	v_rcp_f32_e32 v222, v222
	v_rcp_f32_e32 v223, v223
	v_lshlrev_b32_e32 v242, 16, v190
	v_and_b32_e32 v243, 0xffff0000, v190
	v_lshlrev_b32_e32 v244, 16, v191
	v_and_b32_e32 v245, 0xffff0000, v191
	v_lshlrev_b32_e32 v246, 16, v192
	v_and_b32_e32 v247, 0xffff0000, v192
	v_lshlrev_b32_e32 v248, 16, v193
	v_and_b32_e32 v249, 0xffff0000, v193
	v_pk_mul_f32 v[242:243], v[242:243], s[86:87] op_sel_hi:[1,0]
	v_pk_mul_f32 v[244:245], v[244:245], s[86:87] op_sel_hi:[1,0]
	v_pk_mul_f32 v[246:247], v[246:247], s[86:87] op_sel_hi:[1,0]
	v_pk_mul_f32 v[248:249], v[248:249], s[86:87] op_sel_hi:[1,0]
	v_exp_f32_e32 v242, v242
	v_exp_f32_e32 v243, v243
	v_exp_f32_e32 v244, v244
	v_exp_f32_e32 v245, v245
	v_exp_f32_e32 v246, v246
	v_exp_f32_e32 v247, v247
	v_exp_f32_e32 v248, v248
	v_exp_f32_e32 v249, v249
	v_pk_add_f32 v[242:243], v[242:243], 1.0 op_sel_hi:[1,0]
	v_pk_add_f32 v[244:245], v[244:245], 1.0 op_sel_hi:[1,0]
	v_pk_add_f32 v[246:247], v[246:247], 1.0 op_sel_hi:[1,0]
	v_pk_add_f32 v[248:249], v[248:249], 1.0 op_sel_hi:[1,0]
	v_pk_mul_f32 v[216:217], v[216:217], v[242:243]
	v_pk_mul_f32 v[218:219], v[218:219], v[244:245]
	v_pk_mul_f32 v[220:221], v[220:221], v[246:247]
	v_pk_mul_f32 v[222:223], v[222:223], v[248:249]
	v_pk_mul_f32 v[6:7], v[6:7], v[216:217]
	v_pk_mul_f32 v[8:9], v[8:9], v[218:219]
	v_pk_mul_f32 v[2:3], v[2:3], v[220:221]
	v_pk_mul_f32 v[4:5], v[4:5], v[222:223]
	s_branch .Lem_done
